# strategy 8: GLA-out 48-MFMA chain fed from a 7-slot fragment ring read six ds_reads ahead (was ds_read;lgkmcnt(0);mfma per step)
# baseline (speedup 1.0000x reference)
; DI f32x4 mfma16(bf16x8 a, bf16x8 b, f32x4 c) { return __builtin_amdgcn_mfma_f32_16x16x32_bf16(a, b, c, 0, 0, 0); }
; DI bf16x8 pack8(f32x4 a, f32x4 b) { u32x4 v; v.x = pk2(a[0], a[1]); v.y = pk2(a[2], a[3]); v.z = pk2(b[0], b[1]); v.w = pk2(b[2], b[3]); return __builtin_bit_cast(bf16x8, v); }
; DI void go_compute(int l, const unsigned char* base, const bf16x8 (&qq)[4], int item, int tb, int lane) {
;     ...
;     for (int sb = 0; sb < 4; ++sb) {
;         const unsigned char* kf = base + GO_KF + (16 * sb + c) * 144 + g * 16; const unsigned char* kb = base + GO_KB + (16 * sb + c) * 144 + g * 16;
;         f32x4 f = {0.f, 0.f, 0.f, 0.f}, bk = {0.f, 0.f, 0.f, 0.f};
;         f = mfma16(*(const bf16x8*)kf, qf0, f); f = mfma16(*(const bf16x8*)(kf + 64), qf1, f);
;         bk = mfma16(*(const bf16x8*)kb, qb0, bk); bk = mfma16(*(const bf16x8*)(kb + 64), qb1, bk);
; #pragma unroll
;         for (int i = 0; i < 4; ++i) at[sb][i] = (16 * sb + 4 * g + i <= 16 * tb + c) ? f[i] : bk[i];
;     }
;     const bf16x8 p0 = pack8(at[0], at[1]), p1 = pack8(at[2], at[3]);
;     f32x4 o[8]; float ss = 0.f;
; #pragma unroll
;     for (int eb = 0; eb < 8; ++eb) {
;         const unsigned char* vp = base + GO_VT + (g >> 1) * 2048 + (16 * eb + c) * 16 + (g & 1) * 8;
;         const u32x2 v0 = *(const u32x2*)vp, v1 = *(const u32x2*)(vp + 4096), v2 = *(const u32x2*)(vp + 8192), v3 = *(const u32x2*)(vp + 12288);
;         u32x4 a0; a0.x = v0.x; a0.y = v0.y; a0.z = v1.x; a0.w = v1.y; u32x4 a1; a1.x = v2.x; a1.y = v2.y; a1.z = v3.x; a1.w = v3.y;
;         const unsigned char* sfp = base + GO_SF + (16 * eb + c) * 144 + g * 16; const unsigned char* sbp = base + GO_SB + (16 * eb + c) * 144 + g * 16;
;         f32x4 acc = {0.f, 0.f, 0.f, 0.f};
;         acc = mfma16(__builtin_bit_cast(bf16x8, a0), p0, acc); acc = mfma16(__builtin_bit_cast(bf16x8, a1), p1, acc);
;         acc = mfma16(*(const bf16x8*)sfp, qf0, acc); acc = mfma16(*(const bf16x8*)(sfp + 64), qf1, acc);
.LBB0_873:
	v_readlane_b32 s8, v244, 9
	s_add_i32 s8, s8, s31
	v_readlane_b32 s12, v246, 63
	s_or_b32 s8, s8, s12
	s_movk_i32 s12, 0xa8
	ds_read_b128 v[98:101], v161
	ds_read_b128 v[102:105], v161 offset:64
	s_ashr_i32 s13, s12, 31
	s_add_u32 s12, s0, s12
	s_addc_u32 s13, s1, s13
	s_load_dwordx2 s[40:41], s[12:13], 0x0
	s_waitcnt lgkmcnt(0)
	v_mfma_f32_16x16x32_bf16 v[98:101], v[98:101], v[94:97], 0
	ds_read_b128 v[106:109], v161 offset:9280
	s_ashr_i32 s12, s8, 8
	s_ashr_i32 s13, s12, 31
	v_mfma_f32_16x16x32_bf16 v[98:101], v[102:105], v[90:93], v[98:101]
	ds_read_b128 v[102:105], v161 offset:9216
	s_and_b32 s8, s30, 0xfc0
	s_lshl_b64 s[12:13], s[12:13], 12
	s_or_b32 s8, s12, s8
	s_movk_i32 s12, 0x68
	s_waitcnt lgkmcnt(0)
	v_mfma_f32_16x16x32_bf16 v[102:105], v[102:105], v[86:89], 0
	v_mfma_f32_16x16x32_bf16 v[102:105], v[106:109], v[82:85], v[102:105]
	ds_read_b128 v[106:109], v161 offset:11584
	s_nop 6
	v_cndmask_b32_e64 v0, v98, v102, s[42:43]
	v_cndmask_b32_e64 v110, v103, v99, s[44:45]
	v_cndmask_b32_e64 v111, v100, v104, s[46:47]
	v_cndmask_b32_e64 v112, v101, v105, s[48:49]
	ds_read_b128 v[98:101], v161 offset:2304
	ds_read_b128 v[102:105], v161 offset:2368
	s_waitcnt lgkmcnt(1)
	v_mfma_f32_16x16x32_bf16 v[98:101], v[98:101], v[94:97], 0
	v_cvt_pk_bf16_f32 v114, v0, v110
	v_add_u32_e32 v0, v145, v147
	v_cvt_pk_bf16_f32 v115, v111, v112
	s_waitcnt lgkmcnt(0)
	v_mfma_f32_16x16x32_bf16 v[98:101], v[102:105], v[90:93], v[98:101]
	ds_read_b128 v[102:105], v161 offset:11520
	s_waitcnt lgkmcnt(0)
	v_mfma_f32_16x16x32_bf16 v[102:105], v[102:105], v[86:89], 0
	v_mfma_f32_16x16x32_bf16 v[102:105], v[106:109], v[82:85], v[102:105]
	ds_read_b128 v[106:109], v161 offset:13888
	s_nop 6
	v_cndmask_b32_e64 v113, v98, v102, s[50:51]
	v_cndmask_b32_e64 v116, v99, v103, s[52:53]
	v_cndmask_b32_e64 v117, v100, v104, s[54:55]
	v_cndmask_b32_e64 v118, v101, v105, s[56:57]
	ds_read_b128 v[98:101], v161 offset:4608
	ds_read_b128 v[102:105], v161 offset:4672
	s_waitcnt lgkmcnt(1)
	v_mfma_f32_16x16x32_bf16 v[98:101], v[98:101], v[94:97], 0
	v_cvt_pk_bf16_f32 v117, v117, v118
	v_cvt_pk_bf16_f32 v116, v113, v116
	s_waitcnt lgkmcnt(0)
	v_mfma_f32_16x16x32_bf16 v[98:101], v[102:105], v[90:93], v[98:101]
	ds_read_b128 v[102:105], v161 offset:13824
	s_waitcnt lgkmcnt(0)
	v_mfma_f32_16x16x32_bf16 v[102:105], v[102:105], v[86:89], 0
	v_mfma_f32_16x16x32_bf16 v[102:105], v[106:109], v[82:85], v[102:105]
	ds_read_b128 v[106:109], v162 offset:9280
	s_nop 6
	v_cndmask_b32_e64 v119, v98, v102, s[58:59]
	v_cndmask_b32_e64 v120, v99, v103, s[60:61]
	v_cndmask_b32_e64 v121, v100, v104, s[62:63]
	v_cndmask_b32_e64 v122, v101, v105, s[64:65]
	ds_read_b128 v[98:101], v162
	ds_read_b128 v[102:105], v162 offset:64
	s_waitcnt lgkmcnt(1)
	v_mfma_f32_16x16x32_bf16 v[98:101], v[98:101], v[94:97], 0
	v_cvt_pk_bf16_f32 v118, v119, v120
	v_cvt_pk_bf16_f32 v119, v121, v122
	s_waitcnt lgkmcnt(0)
	v_mfma_f32_16x16x32_bf16 v[98:101], v[102:105], v[90:93], v[98:101]
	ds_read_b128 v[102:105], v162 offset:9216
	s_waitcnt lgkmcnt(0)
	v_mfma_f32_16x16x32_bf16 v[102:105], v[102:105], v[86:89], 0
	v_mfma_f32_16x16x32_bf16 v[102:105], v[106:109], v[82:85], v[102:105]
	s_nop 7
	v_cndmask_b32_e64 v98, v98, v102, s[66:67]
	v_cndmask_b32_e64 v99, v99, v103, s[68:69]
	v_cndmask_b32_e64 v100, v100, v104, s[70:71]
	v_cndmask_b32_e64 v101, v101, v105, s[72:73]
	v_cvt_pk_bf16_f32 v120, v98, v99
	v_cvt_pk_bf16_f32 v121, v100, v101
	ds_read2st64_b64 v[208:211], v0 offset0:36 offset1:44
	ds_read2st64_b64 v[212:215], v0 offset0:52 offset1:60
	ds_read_b128 v[216:219], v161 offset:34816
	ds_read_b128 v[220:223], v161 offset:34880
	ds_read_b128 v[224:227], v161 offset:53248
	ds_read_b128 v[228:231], v161 offset:53312
	s_waitcnt lgkmcnt(5)
	v_mfma_f32_16x16x32_bf16 v[98:101], v[208:211], v[114:117], 0
	ds_read2st64_b64 v[232:235], v163 offset0:36 offset1:44
	s_waitcnt lgkmcnt(5)
	v_mfma_f32_16x16x32_bf16 v[98:101], v[212:215], v[118:121], v[98:101]
	ds_read2st64_b64 v[208:211], v163 offset0:52 offset1:60
	s_waitcnt lgkmcnt(5)
	v_mfma_f32_16x16x32_bf16 v[98:101], v[216:219], v[94:97], v[98:101]
	ds_read_b128 v[212:215], v161 offset:37120
	s_waitcnt lgkmcnt(5)
	v_mfma_f32_16x16x32_bf16 v[98:101], v[220:223], v[90:93], v[98:101]
	ds_read_b128 v[216:219], v161 offset:37184
	s_waitcnt lgkmcnt(5)
	v_mfma_f32_16x16x32_bf16 v[98:101], v[224:227], v[86:89], v[98:101]
	ds_read_b128 v[220:223], v161 offset:55552
	s_waitcnt lgkmcnt(5)
	v_mfma_f32_16x16x32_bf16 v[98:101], v[228:231], v[82:85], v[98:101]
	ds_read_b128 v[224:227], v161 offset:55616
	s_waitcnt lgkmcnt(5)
	v_mfma_f32_16x16x32_bf16 v[102:105], v[232:235], v[114:117], 0
	ds_read2st64_b64 v[228:231], v178 offset0:36 offset1:44
	s_waitcnt lgkmcnt(5)
	v_mfma_f32_16x16x32_bf16 v[102:105], v[208:211], v[118:121], v[102:105]
	ds_read2st64_b64 v[232:235], v178 offset0:52 offset1:60
	s_waitcnt lgkmcnt(5)
	v_mfma_f32_16x16x32_bf16 v[102:105], v[212:215], v[94:97], v[102:105]
	ds_read_b128 v[208:211], v161 offset:39424
	v_mul_f32_e32 v240, v99, v99
	v_mul_f32_e32 v241, v101, v101
	v_fmac_f32_e32 v240, v98, v98
	v_fmac_f32_e32 v241, v100, v100
	v_add_f32_e32 v240, v240, v241
	v_mov_b32_e32 v242, v240
	s_waitcnt lgkmcnt(5)
	v_mfma_f32_16x16x32_bf16 v[102:105], v[216:219], v[90:93], v[102:105]
	ds_read_b128 v[212:215], v161 offset:39488
	s_waitcnt lgkmcnt(5)
	v_mfma_f32_16x16x32_bf16 v[102:105], v[220:223], v[86:89], v[102:105]
	ds_read_b128 v[216:219], v161 offset:57856
	s_waitcnt lgkmcnt(5)
	v_mfma_f32_16x16x32_bf16 v[102:105], v[224:227], v[82:85], v[102:105]
	ds_read_b128 v[220:223], v161 offset:57920
	s_waitcnt lgkmcnt(5)
; DI f32x4 mfma16(bf16x8 a, bf16x8 b, f32x4 c) { return __builtin_amdgcn_mfma_f32_16x16x32_bf16(a, b, c, 0, 0, 0); }
; DI void go_compute(int l, const unsigned char* base, const bf16x8 (&qq)[4], int item, int tb, int lane) {
;     ...
; #pragma unroll
;     for (int eb = 0; eb < 8; ++eb) {
;         const unsigned char* vp = base + GO_VT + (g >> 1) * 2048 + (16 * eb + c) * 16 + (g & 1) * 8;
;         const u32x2 v0 = *(const u32x2*)vp, v1 = *(const u32x2*)(vp + 4096), v2 = *(const u32x2*)(vp + 8192), v3 = *(const u32x2*)(vp + 12288);
;         u32x4 a0; a0.x = v0.x; a0.y = v0.y; a0.z = v1.x; a0.w = v1.y; u32x4 a1; a1.x = v2.x; a1.y = v2.y; a1.z = v3.x; a1.w = v3.y;
;         const unsigned char* sfp = base + GO_SF + (16 * eb + c) * 144 + g * 16; const unsigned char* sbp = base + GO_SB + (16 * eb + c) * 144 + g * 16;
;         f32x4 acc = {0.f, 0.f, 0.f, 0.f};
;         acc = mfma16(__builtin_bit_cast(bf16x8, a0), p0, acc); acc = mfma16(__builtin_bit_cast(bf16x8, a1), p1, acc);
;         acc = mfma16(*(const bf16x8*)sfp, qf0, acc); acc = mfma16(*(const bf16x8*)(sfp + 64), qf1, acc);
;         acc = mfma16(*(const bf16x8*)sbp, qb0, acc); acc = mfma16(*(const bf16x8*)(sbp + 64), qb1, acc);
;         o[eb] = acc; ss += (acc[0] * acc[0] + acc[1] * acc[1]) + (acc[2] * acc[2] + acc[3] * acc[3]);
	v_mfma_f32_16x16x32_bf16 v[106:109], v[228:231], v[114:117], 0
	ds_read2st64_b64 v[224:227], v179 offset0:36 offset1:44
	s_waitcnt lgkmcnt(5)
	v_mfma_f32_16x16x32_bf16 v[106:109], v[232:235], v[118:121], v[106:109]
	ds_read2st64_b64 v[228:231], v179 offset0:52 offset1:60
	s_waitcnt lgkmcnt(5)
	v_mfma_f32_16x16x32_bf16 v[106:109], v[208:211], v[94:97], v[106:109]
	ds_read_b128 v[232:235], v162 offset:34816
	v_mul_f32_e32 v240, v103, v103
	v_mul_f32_e32 v241, v105, v105
	v_fmac_f32_e32 v240, v102, v102
	v_fmac_f32_e32 v241, v104, v104
	v_add_f32_e32 v240, v240, v241
	v_add_f32_e32 v242, v242, v240
	s_waitcnt lgkmcnt(5)
	v_mfma_f32_16x16x32_bf16 v[106:109], v[212:215], v[90:93], v[106:109]
	ds_read_b128 v[208:211], v162 offset:34880
	s_waitcnt lgkmcnt(5)
	v_mfma_f32_16x16x32_bf16 v[106:109], v[216:219], v[86:89], v[106:109]
	ds_read_b128 v[212:215], v162 offset:53248
	s_waitcnt lgkmcnt(5)
	v_mfma_f32_16x16x32_bf16 v[106:109], v[220:223], v[82:85], v[106:109]
	ds_read_b128 v[216:219], v162 offset:53312
	s_waitcnt lgkmcnt(5)
	v_mfma_f32_16x16x32_bf16 v[110:113], v[224:227], v[114:117], 0
	ds_read2st64_b64 v[220:223], v180 offset0:36 offset1:44
	s_waitcnt lgkmcnt(5)
	v_mfma_f32_16x16x32_bf16 v[110:113], v[228:231], v[118:121], v[110:113]
	ds_read2st64_b64 v[224:227], v180 offset0:52 offset1:60
	s_waitcnt lgkmcnt(5)
	v_mfma_f32_16x16x32_bf16 v[110:113], v[232:235], v[94:97], v[110:113]
	ds_read_b128 v[228:231], v181 offset:34816
	v_mul_f32_e32 v240, v107, v107
	v_mul_f32_e32 v241, v109, v109
	v_fmac_f32_e32 v240, v106, v106
	v_fmac_f32_e32 v241, v108, v108
	v_add_f32_e32 v240, v240, v241
	v_add_f32_e32 v242, v242, v240
	s_waitcnt lgkmcnt(5)
	v_mfma_f32_16x16x32_bf16 v[110:113], v[208:211], v[90:93], v[110:113]
	ds_read_b128 v[232:235], v181 offset:34880
	s_waitcnt lgkmcnt(5)
	v_mfma_f32_16x16x32_bf16 v[110:113], v[212:215], v[86:89], v[110:113]
	ds_read_b128 v[208:211], v181 offset:53248
	s_waitcnt lgkmcnt(5)
	v_mfma_f32_16x16x32_bf16 v[110:113], v[216:219], v[82:85], v[110:113]
	ds_read_b128 v[212:215], v181 offset:53312
	s_waitcnt lgkmcnt(5)
	v_mfma_f32_16x16x32_bf16 v[122:125], v[220:223], v[114:117], 0
	ds_read2st64_b64 v[216:219], v182 offset0:36 offset1:44
	s_waitcnt lgkmcnt(5)
	v_mfma_f32_16x16x32_bf16 v[122:125], v[224:227], v[118:121], v[122:125]
	ds_read2st64_b64 v[220:223], v182 offset0:52 offset1:60
	s_waitcnt lgkmcnt(5)
	v_mfma_f32_16x16x32_bf16 v[122:125], v[228:231], v[94:97], v[122:125]
	ds_read_b128 v[224:227], v181 offset:37120
	v_mul_f32_e32 v240, v111, v111
	v_mul_f32_e32 v241, v113, v113
	v_fmac_f32_e32 v240, v110, v110
	v_fmac_f32_e32 v241, v112, v112
	v_add_f32_e32 v240, v240, v241
	v_add_f32_e32 v242, v242, v240
	s_waitcnt lgkmcnt(5)
	v_mfma_f32_16x16x32_bf16 v[122:125], v[232:235], v[90:93], v[122:125]
	ds_read_b128 v[228:231], v181 offset:37184
	s_waitcnt lgkmcnt(5)
	v_mfma_f32_16x16x32_bf16 v[122:125], v[208:211], v[86:89], v[122:125]
	ds_read_b128 v[232:235], v181 offset:55552
	s_waitcnt lgkmcnt(5)
	v_mfma_f32_16x16x32_bf16 v[122:125], v[212:215], v[82:85], v[122:125]
	ds_read_b128 v[208:211], v181 offset:55616
	s_waitcnt lgkmcnt(5)
	v_mfma_f32_16x16x32_bf16 v[126:129], v[216:219], v[114:117], 0
	ds_read2st64_b64 v[212:215], v183 offset0:36 offset1:44
	s_waitcnt lgkmcnt(5)
	v_mfma_f32_16x16x32_bf16 v[126:129], v[220:223], v[118:121], v[126:129]
	ds_read2st64_b64 v[216:219], v183 offset0:52 offset1:60
	s_waitcnt lgkmcnt(5)
	v_mfma_f32_16x16x32_bf16 v[126:129], v[224:227], v[94:97], v[126:129]
	ds_read_b128 v[220:223], v181 offset:39424
	v_mul_f32_e32 v240, v123, v123
	v_mul_f32_e32 v241, v125, v125
	v_fmac_f32_e32 v240, v122, v122
	v_fmac_f32_e32 v241, v124, v124
	v_add_f32_e32 v240, v240, v241
	v_add_f32_e32 v242, v242, v240
	s_waitcnt lgkmcnt(5)
	v_mfma_f32_16x16x32_bf16 v[126:129], v[228:231], v[90:93], v[126:129]
	ds_read_b128 v[224:227], v181 offset:39488
	s_waitcnt lgkmcnt(5)
	v_mfma_f32_16x16x32_bf16 v[126:129], v[232:235], v[86:89], v[126:129]
	ds_read_b128 v[228:231], v181 offset:57856
	s_waitcnt lgkmcnt(5)
	v_mfma_f32_16x16x32_bf16 v[126:129], v[208:211], v[82:85], v[126:129]
	ds_read_b128 v[232:235], v181 offset:57920
	s_waitcnt lgkmcnt(5)
	v_mfma_f32_16x16x32_bf16 v[130:133], v[212:215], v[114:117], 0
	ds_read2st64_b64 v[208:211], v184 offset0:36 offset1:44
	s_waitcnt lgkmcnt(5)
	v_mfma_f32_16x16x32_bf16 v[130:133], v[216:219], v[118:121], v[130:133]
	ds_read2st64_b64 v[212:215], v184 offset0:52 offset1:60
	s_waitcnt lgkmcnt(5)
	v_mfma_f32_16x16x32_bf16 v[130:133], v[220:223], v[94:97], v[130:133]
	ds_read_b128 v[216:219], v185 offset:34816
	v_mul_f32_e32 v240, v127, v127
	v_mul_f32_e32 v241, v129, v129
	v_fmac_f32_e32 v240, v126, v126
	v_fmac_f32_e32 v241, v128, v128
	v_add_f32_e32 v240, v240, v241
	v_add_f32_e32 v242, v242, v240
	s_waitcnt lgkmcnt(5)
	v_mfma_f32_16x16x32_bf16 v[130:133], v[224:227], v[90:93], v[130:133]
	ds_read_b128 v[220:223], v185 offset:34880
	s_waitcnt lgkmcnt(5)
	v_mfma_f32_16x16x32_bf16 v[130:133], v[228:231], v[86:89], v[130:133]
	ds_read_b128 v[224:227], v185 offset:53248
	s_waitcnt lgkmcnt(5)
	v_mfma_f32_16x16x32_bf16 v[130:133], v[232:235], v[82:85], v[130:133]
	ds_read_b128 v[228:231], v185 offset:53312
	s_waitcnt lgkmcnt(5)
	v_mfma_f32_16x16x32_bf16 v[236:239], v[208:211], v[114:117], 0
	s_waitcnt lgkmcnt(4)
	v_mfma_f32_16x16x32_bf16 v[236:239], v[212:215], v[118:121], v[236:239]
	s_waitcnt lgkmcnt(3)
	v_mfma_f32_16x16x32_bf16 v[236:239], v[216:219], v[94:97], v[236:239]
	v_mul_f32_e32 v240, v131, v131
	v_mul_f32_e32 v241, v133, v133
	v_fmac_f32_e32 v240, v130, v130
	v_fmac_f32_e32 v241, v132, v132
	v_add_f32_e32 v240, v240, v241
	v_add_f32_e32 v242, v242, v240
	s_waitcnt lgkmcnt(2)
; DI unsigned pk2(float lo, float hi) { return pg8::cvt_pk_bf16(lo, hi); }
; DI float bflo(unsigned w) { return __uint_as_float(w << 16); }
; DI float bfhi(unsigned w) { return __uint_as_float(w & 0xffff0000u); }
; DI f32x4 mfma16(bf16x8 a, bf16x8 b, f32x4 c) { return __builtin_amdgcn_mfma_f32_16x16x32_bf16(a, b, c, 0, 0, 0); }
; DI float silu_f(float x) { return x * __builtin_amdgcn_rcpf(1.0f + __expf(-x)); }
; #define INP(i) ((const float*)karg(8 * (i)))
; DI void go_compute(int l, const unsigned char* base, const bf16x8 (&qq)[4], int item, int tb, int lane) {
;     ...
;         f32x4 acc = {0.f, 0.f, 0.f, 0.f};
;         acc = mfma16(__builtin_bit_cast(bf16x8, a0), p0, acc); acc = mfma16(__builtin_bit_cast(bf16x8, a1), p1, acc);
;         acc = mfma16(*(const bf16x8*)sfp, qf0, acc); acc = mfma16(*(const bf16x8*)(sfp + 64), qf1, acc);
;         acc = mfma16(*(const bf16x8*)sbp, qb0, acc); acc = mfma16(*(const bf16x8*)(sbp + 64), qb1, acc);
;         o[eb] = acc; ss += (acc[0] * acc[0] + acc[1] * acc[1]) + (acc[2] * acc[2] + acc[3] * acc[3]);
;     }
;     ss += __shfl_xor(ss, 16); ss += __shfl_xor(ss, 32);
;     const float rstd = rsqrtf(ss * (1.0f / 128.0f) + EPS);
;     const float* gain = INP(13) + l * 128 + 4 * g;
;     const size_t tok = tok0 + 16 * tb + c;
; #pragma unroll
;     for (int eb = 0; eb < 8; ++eb) {
;         const f32x4 gn = *(const f32x4*)(gain + 16 * eb);
;         const u32x2 gr = *(const u32x2*)(GR + tok * 512 + h * 128 + 16 * eb + 4 * g);
;         const float r0 = bflo(gr.x), r1 = bfhi(gr.x), r2 = bflo(gr.y), r3 = bfhi(gr.y);
;         u32x2 w; w.x = pk2(o[eb][0] * rstd * gn[0] * silu_f(r0), o[eb][1] * rstd * gn[1] * silu_f(r1)); w.y = pk2(o[eb][2] * rstd * gn[2] * silu_f(r2), o[eb][3] * rstd * gn[3] * silu_f(r3));
;         *(u32x2*)(MIX + tok * 1024 + 512 + h * 128 + 16 * eb + 4 * g) = w;
	v_mfma_f32_16x16x32_bf16 v[236:239], v[220:223], v[90:93], v[236:239]
	s_waitcnt lgkmcnt(1)
	v_mfma_f32_16x16x32_bf16 v[236:239], v[224:227], v[86:89], v[236:239]
	s_waitcnt lgkmcnt(0)
	v_mfma_f32_16x16x32_bf16 v[82:85], v[228:231], v[82:85], v[236:239]
	s_nop 7
	v_mul_f32_e32 v240, v83, v83
	v_mul_f32_e32 v241, v85, v85
	v_fmac_f32_e32 v240, v82, v82
	v_fmac_f32_e32 v241, v84, v84
	v_add_f32_e32 v240, v240, v241
	v_add_f32_e32 v242, v242, v240
	s_ashr_i32 s15, s12, 31
	s_add_u32 s14, s0, s12
	s_addc_u32 s15, s1, s15
	s_load_dwordx2 s[14:15], s[14:15], 0x0
	v_lshlrev_b32_e32 v91, 2, v152
	v_mov_b32_e32 v0, v242
	v_and_b32_e32 v87, 64, v194
	v_xor_b32_e32 v86, 16, v194
	v_add_u32_e32 v87, 64, v87
	v_cmp_lt_i32_e32 vcc, v86, v87
	s_waitcnt lgkmcnt(0)
	s_add_u32 s14, s14, s2
	s_addc_u32 s15, s15, s3
	v_cndmask_b32_e32 v86, v194, v86, vcc
	v_lshlrev_b32_e32 v86, 2, v86
	ds_bpermute_b32 v86, v86, v0
	s_waitcnt lgkmcnt(0)
	v_add_f32_e32 v0, v0, v86
	v_xor_b32_e32 v86, 32, v194
	v_cmp_lt_i32_e32 vcc, v86, v87
	v_mov_b32_e32 v87, s13
	s_mov_b64 s[12:13], 0x11600000
	v_cndmask_b32_e32 v86, v194, v86, vcc
	v_lshlrev_b32_e32 v86, 2, v86
	ds_bpermute_b32 v86, v86, v0
	s_waitcnt lgkmcnt(0)
	v_add_f32_e32 v0, v0, v86
	v_fmamk_f32 v0, v0, 0x3c000000, v164
	v_cmp_gt_f32_e32 vcc, s25, v0
	v_mul_f32_e32 v86, 0x4b800000, v0
	s_nop 0
	v_cndmask_b32_e32 v0, v0, v86, vcc
	v_rsq_f32_e32 v0, v0
	s_nop 0
	v_mul_f32_e32 v86, 0x45800000, v0
	v_cndmask_b32_e32 v90, v0, v86, vcc
	v_or_b32_e32 v86, s8, v148
	v_lshlrev_b64 v[88:89], 10, v[86:87]
	s_and_b32 s8, s29, 0x180
	v_lshl_add_u64 v[88:89], s[40:41], 0, v[88:89]
	s_lshl_b32 s8, s8, 1
	v_lshlrev_b64 v[86:87], 11, v[86:87]
	v_lshl_add_u64 v[88:89], v[88:89], 0, s[8:9]
	v_lshlrev_b32_e32 v0, 1, v152
	v_lshl_add_u64 v[86:87], s[40:41], 0, v[86:87]
	v_lshl_add_u64 v[96:97], v[88:89], 0, v[0:1]
	v_lshl_add_u64 v[86:87], v[86:87], 0, s[8:9]
	s_mov_b32 s8, 0x11600000
	v_lshl_add_u64 v[94:95], v[96:97], 0, s[12:13]
	v_add_co_u32_e32 v96, vcc, s8, v96
	v_lshl_add_u64 v[114:115], v[86:87], 0, v[0:1]
	s_nop 0
	v_addc_co_u32_e32 v97, vcc, 0, v97, vcc
	v_pk_mul_f32 v[98:99], v[98:99], v[90:91] op_sel_hi:[1,0]
	global_load_dwordx4 v[208:211], v91, s[14:15]
	global_load_dwordx4 v[212:215], v91, s[14:15] offset:64
	global_load_dwordx4 v[216:219], v91, s[14:15] offset:128
	global_load_dwordx4 v[220:223], v91, s[14:15] offset:192
	global_load_dwordx4 v[224:227], v91, s[14:15] offset:256
	global_load_dwordx4 v[228:231], v91, s[14:15] offset:320
	global_load_dwordx4 v[232:235], v91, s[14:15] offset:384
	global_load_dwordx4 v[236:239], v91, s[14:15] offset:448
	global_load_dwordx2 v[240:241], v[94:95], off
	global_load_dwordx2 v[242:243], v[94:95], off offset:32
	v_pk_mul_f32 v[100:101], v[100:101], v[90:91] op_sel_hi:[1,0]
	s_mov_b32 s8, 0x1b600000
	v_pk_mul_f32 v[102:103], v[102:103], v[90:91] op_sel_hi:[1,0]
	s_mov_b64 s[12:13], 0x1b600400
	v_lshl_add_u64 v[92:93], v[114:115], 0, s[12:13]
	v_pk_mul_f32 v[82:83], v[82:83], v[90:91] op_sel_hi:[1,0]
	v_pk_mul_f32 v[84:85], v[84:85], v[90:91] op_sel_hi:[1,0]
	s_waitcnt vmcnt(1)
	s_nop 1
	v_mov_b32_e32 v86, v208
	v_mov_b32_e32 v87, v209
	v_mov_b32_e32 v88, v210
	v_mov_b32_e32 v89, v211
	v_mov_b32_e32 v96, v240
	v_mov_b32_e32 v97, v241
	global_load_dwordx2 v[240:241], v[94:95], off offset:64
	v_lshlrev_b32_e32 v116, 16, v96
	v_mul_f32_e32 v0, 0xbfb8aa3b, v116
	v_exp_f32_e32 v0, v0
	v_and_b32_e32 v117, 0xffff0000, v96
	v_lshlrev_b32_e32 v96, 16, v97
	v_pk_mul_f32 v[86:87], v[86:87], v[98:99]
	v_add_f32_e32 v0, 1.0, v0
	v_rcp_f32_e32 v118, v0
	v_mul_f32_e32 v0, 0xbfb8aa3b, v117
	v_exp_f32_e32 v0, v0
	v_and_b32_e32 v97, 0xffff0000, v97
	v_pk_mul_f32 v[88:89], v[88:89], v[100:101]
	v_add_f32_e32 v0, 1.0, v0
	v_rcp_f32_e32 v119, v0
	v_mul_f32_e32 v0, 0xbfb8aa3b, v96
	v_exp_f32_e32 v0, v0
	v_pk_mul_f32 v[98:99], v[118:119], v[116:117]
	s_nop 0
	v_pk_mul_f32 v[86:87], v[86:87], v[98:99]
	v_add_f32_e32 v0, 1.0, v0
	v_rcp_f32_e32 v98, v0
	v_mul_f32_e32 v0, 0xbfb8aa3b, v97
	v_exp_f32_e32 v0, v0
	v_cvt_pk_bf16_f32 v86, v86, v87
	v_add_f32_e32 v0, 1.0, v0
	v_rcp_f32_e32 v99, v0
	s_nop 0
	v_pk_mul_f32 v[96:97], v[98:99], v[96:97]
	s_nop 0
	v_pk_mul_f32 v[88:89], v[88:89], v[96:97]
	s_nop 0
	v_cvt_pk_bf16_f32 v87, v88, v89
	v_add_co_u32_e32 v88, vcc, s8, v114
	v_readlane_b32 s8, v244, 5
	s_nop 0
	v_addc_co_u32_e32 v89, vcc, 0, v115, vcc
	global_store_dwordx2 v[88:89], v[86:87], off offset:1024
	s_nop 0
	s_add_i32 s29, s29, s8
	v_readlane_b32 s8, v244, 8
	s_add_i32 s30, s30, s8
	v_readlane_b32 s8, v244, 10
	s_add_i32 s31, s31, s8
	s_andn2_b64 vcc, exec, s[38:39]
	s_waitcnt vmcnt(2)
	s_nop 1
	v_mov_b32_e32 v86, v212
	v_mov_b32_e32 v87, v213
	v_mov_b32_e32 v88, v214
	v_mov_b32_e32 v89, v215
	v_mov_b32_e32 v96, v242
	v_mov_b32_e32 v97, v243
	global_load_dwordx2 v[242:243], v[94:95], off offset:96
	v_pk_mul_f32 v[86:87], v[86:87], v[102:103]
	v_lshlrev_b32_e32 v98, 16, v96
	v_mul_f32_e32 v0, 0xbfb8aa3b, v98
	v_exp_f32_e32 v0, v0
	v_and_b32_e32 v99, 0xffff0000, v96
	v_lshlrev_b32_e32 v96, 16, v97
	v_and_b32_e32 v97, 0xffff0000, v97
	v_add_f32_e32 v0, 1.0, v0
	v_rcp_f32_e32 v100, v0
	v_mul_f32_e32 v0, 0xbfb8aa3b, v99
	v_exp_f32_e32 v0, v0
	v_pk_mul_f32 v[102:103], v[106:107], v[90:91] op_sel_hi:[1,0]
	v_add_f32_e32 v0, 1.0, v0
	v_rcp_f32_e32 v101, v0
	v_mul_f32_e32 v0, 0xbfb8aa3b, v96
	v_exp_f32_e32 v0, v0
	v_pk_mul_f32 v[98:99], v[100:101], v[98:99]
	s_nop 0
	v_pk_mul_f32 v[86:87], v[86:87], v[98:99]
	v_add_f32_e32 v0, 1.0, v0
	v_rcp_f32_e32 v98, v0
	v_mul_f32_e32 v0, 0xbfb8aa3b, v97
	v_exp_f32_e32 v0, v0
	v_pk_mul_f32 v[100:101], v[104:105], v[90:91] op_sel_hi:[1,0]
	v_cvt_pk_bf16_f32 v86, v86, v87
	v_pk_mul_f32 v[88:89], v[88:89], v[100:101]
	v_add_f32_e32 v0, 1.0, v0
	v_rcp_f32_e32 v99, v0
	s_nop 0
	v_pk_mul_f32 v[96:97], v[98:99], v[96:97]
	s_nop 0
	v_pk_mul_f32 v[88:89], v[88:89], v[96:97]
	s_nop 0
	v_cvt_pk_bf16_f32 v87, v88, v89
	global_store_dwordx2 v[92:93], v[86:87], off offset:32
	s_nop 0
	s_waitcnt vmcnt(3)
; DI unsigned pk2(float lo, float hi) { return pg8::cvt_pk_bf16(lo, hi); }
; DI float bflo(unsigned w) { return __uint_as_float(w << 16); }
; DI float bfhi(unsigned w) { return __uint_as_float(w & 0xffff0000u); }
; DI float silu_f(float x) { return x * __builtin_amdgcn_rcpf(1.0f + __expf(-x)); }
; DI void go_compute(int l, const unsigned char* base, const bf16x8 (&qq)[4], int item, int tb, int lane) {
;     ...
; #pragma unroll
;     for (int eb = 0; eb < 8; ++eb) {
;         const f32x4 gn = *(const f32x4*)(gain + 16 * eb);
;         const u32x2 gr = *(const u32x2*)(GR + tok * 512 + h * 128 + 16 * eb + 4 * g);
;         const float r0 = bflo(gr.x), r1 = bfhi(gr.x), r2 = bflo(gr.y), r3 = bfhi(gr.y);
;         u32x2 w; w.x = pk2(o[eb][0] * rstd * gn[0] * silu_f(r0), o[eb][1] * rstd * gn[1] * silu_f(r1)); w.y = pk2(o[eb][2] * rstd * gn[2] * silu_f(r2), o[eb][3] * rstd * gn[3] * silu_f(r3));
;         *(u32x2*)(MIX + tok * 1024 + 512 + h * 128 + 16 * eb + 4 * g) = w;
	s_nop 1
	v_mov_b32_e32 v86, v216
	v_mov_b32_e32 v87, v217
	v_mov_b32_e32 v88, v218
	v_mov_b32_e32 v89, v219
	v_mov_b32_e32 v96, v240
	v_mov_b32_e32 v97, v241
	global_load_dwordx2 v[240:241], v[94:95], off offset:128
	v_pk_mul_f32 v[86:87], v[86:87], v[102:103]
	v_lshlrev_b32_e32 v98, 16, v96
	v_mul_f32_e32 v0, 0xbfb8aa3b, v98
	v_exp_f32_e32 v0, v0
	v_and_b32_e32 v99, 0xffff0000, v96
	v_lshlrev_b32_e32 v96, 16, v97
	v_and_b32_e32 v97, 0xffff0000, v97
	v_add_f32_e32 v0, 1.0, v0
	v_rcp_f32_e32 v100, v0
	v_mul_f32_e32 v0, 0xbfb8aa3b, v99
	v_exp_f32_e32 v0, v0
	v_pk_mul_f32 v[102:103], v[110:111], v[90:91] op_sel_hi:[1,0]
	v_add_f32_e32 v0, 1.0, v0
	v_rcp_f32_e32 v101, v0
	v_mul_f32_e32 v0, 0xbfb8aa3b, v96
	v_exp_f32_e32 v0, v0
	v_pk_mul_f32 v[98:99], v[100:101], v[98:99]
	s_nop 0
	v_pk_mul_f32 v[86:87], v[86:87], v[98:99]
	v_add_f32_e32 v0, 1.0, v0
	v_rcp_f32_e32 v98, v0
	v_mul_f32_e32 v0, 0xbfb8aa3b, v97
	v_exp_f32_e32 v0, v0
	v_pk_mul_f32 v[100:101], v[108:109], v[90:91] op_sel_hi:[1,0]
	v_cvt_pk_bf16_f32 v86, v86, v87
	v_pk_mul_f32 v[88:89], v[88:89], v[100:101]
	v_add_f32_e32 v0, 1.0, v0
	v_rcp_f32_e32 v99, v0
	s_nop 0
	v_pk_mul_f32 v[96:97], v[98:99], v[96:97]
	s_nop 0
	v_pk_mul_f32 v[88:89], v[88:89], v[96:97]
	s_nop 0
	v_cvt_pk_bf16_f32 v87, v88, v89
	global_store_dwordx2 v[92:93], v[86:87], off offset:64
	s_nop 0
	s_waitcnt vmcnt(3)
	s_nop 1
	v_mov_b32_e32 v86, v220
	v_mov_b32_e32 v87, v221
	v_mov_b32_e32 v88, v222
	v_mov_b32_e32 v89, v223
	v_mov_b32_e32 v96, v242
	v_mov_b32_e32 v97, v243
	global_load_dwordx2 v[242:243], v[94:95], off offset:160
	v_pk_mul_f32 v[86:87], v[102:103], v[86:87]
	v_lshlrev_b32_e32 v98, 16, v96
	v_mul_f32_e32 v0, 0xbfb8aa3b, v98
	v_exp_f32_e32 v0, v0
	v_and_b32_e32 v99, 0xffff0000, v96
	v_lshlrev_b32_e32 v96, 16, v97
	v_and_b32_e32 v97, 0xffff0000, v97
	v_add_f32_e32 v0, 1.0, v0
	v_rcp_f32_e32 v100, v0
	v_mul_f32_e32 v0, 0xbfb8aa3b, v99
	v_exp_f32_e32 v0, v0
	v_pk_mul_f32 v[102:103], v[122:123], v[90:91] op_sel_hi:[1,0]
	v_add_f32_e32 v0, 1.0, v0
	v_rcp_f32_e32 v101, v0
	v_mul_f32_e32 v0, 0xbfb8aa3b, v96
	v_exp_f32_e32 v0, v0
	v_pk_mul_f32 v[98:99], v[100:101], v[98:99]
	s_nop 0
	v_pk_mul_f32 v[86:87], v[86:87], v[98:99]
	v_add_f32_e32 v0, 1.0, v0
	v_rcp_f32_e32 v98, v0
	v_mul_f32_e32 v0, 0xbfb8aa3b, v97
	v_exp_f32_e32 v0, v0
	v_pk_mul_f32 v[100:101], v[112:113], v[90:91] op_sel_hi:[1,0]
	v_cvt_pk_bf16_f32 v86, v86, v87
	v_pk_mul_f32 v[88:89], v[100:101], v[88:89]
	v_add_f32_e32 v0, 1.0, v0
	v_rcp_f32_e32 v99, v0
	s_nop 0
	v_pk_mul_f32 v[96:97], v[98:99], v[96:97]
	s_nop 0
	v_pk_mul_f32 v[88:89], v[88:89], v[96:97]
	s_nop 0
	v_cvt_pk_bf16_f32 v87, v88, v89
	global_store_dwordx2 v[92:93], v[86:87], off offset:96
	s_nop 0
	s_waitcnt vmcnt(3)
	s_nop 1
	v_mov_b32_e32 v86, v224
	v_mov_b32_e32 v87, v225
	v_mov_b32_e32 v88, v226
	v_mov_b32_e32 v89, v227
	v_mov_b32_e32 v96, v240
	v_mov_b32_e32 v97, v241
	global_load_dwordx2 v[240:241], v[94:95], off offset:192
	v_pk_mul_f32 v[86:87], v[102:103], v[86:87]
	v_lshlrev_b32_e32 v98, 16, v96
	v_mul_f32_e32 v0, 0xbfb8aa3b, v98
	v_exp_f32_e32 v0, v0
	v_and_b32_e32 v99, 0xffff0000, v96
	v_lshlrev_b32_e32 v96, 16, v97
	v_and_b32_e32 v97, 0xffff0000, v97
	v_add_f32_e32 v0, 1.0, v0
	v_rcp_f32_e32 v100, v0
	v_mul_f32_e32 v0, 0xbfb8aa3b, v99
	v_exp_f32_e32 v0, v0
	v_pk_mul_f32 v[102:103], v[126:127], v[90:91] op_sel_hi:[1,0]
	v_add_f32_e32 v0, 1.0, v0
	v_rcp_f32_e32 v101, v0
	v_mul_f32_e32 v0, 0xbfb8aa3b, v96
	v_exp_f32_e32 v0, v0
	v_pk_mul_f32 v[98:99], v[100:101], v[98:99]
	s_nop 0
	v_pk_mul_f32 v[86:87], v[86:87], v[98:99]
	v_add_f32_e32 v0, 1.0, v0
	v_rcp_f32_e32 v98, v0
	v_mul_f32_e32 v0, 0xbfb8aa3b, v97
	v_exp_f32_e32 v0, v0
	v_pk_mul_f32 v[100:101], v[124:125], v[90:91] op_sel_hi:[1,0]
	v_cvt_pk_bf16_f32 v86, v86, v87
	v_pk_mul_f32 v[88:89], v[100:101], v[88:89]
	v_add_f32_e32 v0, 1.0, v0
	v_rcp_f32_e32 v99, v0
	s_nop 0
	v_pk_mul_f32 v[96:97], v[98:99], v[96:97]
	s_nop 0
	v_pk_mul_f32 v[88:89], v[88:89], v[96:97]
	s_nop 0
	v_cvt_pk_bf16_f32 v87, v88, v89
	global_store_dwordx2 v[92:93], v[86:87], off offset:128
	s_nop 0
	s_waitcnt vmcnt(3)
; DI unsigned pk2(float lo, float hi) { return pg8::cvt_pk_bf16(lo, hi); }
; DI float bflo(unsigned w) { return __uint_as_float(w << 16); }
; DI float bfhi(unsigned w) { return __uint_as_float(w & 0xffff0000u); }
; DI float silu_f(float x) { return x * __builtin_amdgcn_rcpf(1.0f + __expf(-x)); }
; DI void go_compute(int l, const unsigned char* base, const bf16x8 (&qq)[4], int item, int tb, int lane) {
;     ...
; #pragma unroll
;     for (int eb = 0; eb < 8; ++eb) {
;         const f32x4 gn = *(const f32x4*)(gain + 16 * eb);
;         const u32x2 gr = *(const u32x2*)(GR + tok * 512 + h * 128 + 16 * eb + 4 * g);
;         const float r0 = bflo(gr.x), r1 = bfhi(gr.x), r2 = bflo(gr.y), r3 = bfhi(gr.y);
;         u32x2 w; w.x = pk2(o[eb][0] * rstd * gn[0] * silu_f(r0), o[eb][1] * rstd * gn[1] * silu_f(r1)); w.y = pk2(o[eb][2] * rstd * gn[2] * silu_f(r2), o[eb][3] * rstd * gn[3] * silu_f(r3));
;         *(u32x2*)(MIX + tok * 1024 + 512 + h * 128 + 16 * eb + 4 * g) = w;
; DI void gla_out_phase(int l, unsigned char* ldsb, int tid, int wave, int lane, bool xl, int xq, int k0, int kend, int kstep) {
;     ...
;         go_compute(l, base, qq, go_item(xl, xq, k, half), tb, lane);
;         __syncthreads();
	s_nop 1
	v_mov_b32_e32 v86, v228
	v_mov_b32_e32 v87, v229
	v_mov_b32_e32 v88, v230
	v_mov_b32_e32 v89, v231
	v_mov_b32_e32 v96, v242
	v_mov_b32_e32 v97, v243
	global_load_dwordx2 v[242:243], v[94:95], off offset:224
	v_pk_mul_f32 v[86:87], v[102:103], v[86:87]
	v_lshlrev_b32_e32 v98, 16, v96
	v_mul_f32_e32 v0, 0xbfb8aa3b, v98
	v_exp_f32_e32 v0, v0
	v_and_b32_e32 v99, 0xffff0000, v96
	v_lshlrev_b32_e32 v96, 16, v97
	v_and_b32_e32 v97, 0xffff0000, v97
	v_add_f32_e32 v0, 1.0, v0
	v_rcp_f32_e32 v100, v0
	v_mul_f32_e32 v0, 0xbfb8aa3b, v99
	v_exp_f32_e32 v0, v0
	v_pk_mul_f32 v[102:103], v[130:131], v[90:91] op_sel_hi:[1,0]
	v_add_f32_e32 v0, 1.0, v0
	v_rcp_f32_e32 v101, v0
	v_mul_f32_e32 v0, 0xbfb8aa3b, v96
	v_exp_f32_e32 v0, v0
	v_pk_mul_f32 v[98:99], v[100:101], v[98:99]
	s_nop 0
	v_pk_mul_f32 v[86:87], v[86:87], v[98:99]
	v_add_f32_e32 v0, 1.0, v0
	v_rcp_f32_e32 v98, v0
	v_mul_f32_e32 v0, 0xbfb8aa3b, v97
	v_exp_f32_e32 v0, v0
	v_pk_mul_f32 v[100:101], v[128:129], v[90:91] op_sel_hi:[1,0]
	v_cvt_pk_bf16_f32 v86, v86, v87
	v_pk_mul_f32 v[88:89], v[100:101], v[88:89]
	v_add_f32_e32 v0, 1.0, v0
	v_rcp_f32_e32 v99, v0
	s_nop 0
	v_pk_mul_f32 v[96:97], v[98:99], v[96:97]
	s_nop 0
	v_pk_mul_f32 v[88:89], v[88:89], v[96:97]
	s_nop 0
	v_cvt_pk_bf16_f32 v87, v88, v89
	global_store_dwordx2 v[92:93], v[86:87], off offset:160
	s_nop 0
	s_waitcnt vmcnt(3)
	s_nop 1
	v_mov_b32_e32 v86, v232
	v_mov_b32_e32 v87, v233
	v_mov_b32_e32 v88, v234
	v_mov_b32_e32 v89, v235
	v_mov_b32_e32 v96, v240
	v_mov_b32_e32 v97, v241
	v_pk_mul_f32 v[86:87], v[102:103], v[86:87]
	v_lshlrev_b32_e32 v98, 16, v96
	v_mul_f32_e32 v0, 0xbfb8aa3b, v98
	v_exp_f32_e32 v0, v0
	v_and_b32_e32 v99, 0xffff0000, v96
	v_lshlrev_b32_e32 v96, 16, v97
	v_and_b32_e32 v97, 0xffff0000, v97
	v_add_f32_e32 v0, 1.0, v0
	v_rcp_f32_e32 v100, v0
	v_mul_f32_e32 v0, 0xbfb8aa3b, v99
	v_exp_f32_e32 v0, v0
	s_nop 0
	v_add_f32_e32 v0, 1.0, v0
	v_rcp_f32_e32 v101, v0
	v_mul_f32_e32 v0, 0xbfb8aa3b, v96
	v_exp_f32_e32 v0, v0
	v_pk_mul_f32 v[98:99], v[100:101], v[98:99]
	s_nop 0
	v_pk_mul_f32 v[86:87], v[86:87], v[98:99]
	v_add_f32_e32 v0, 1.0, v0
	v_rcp_f32_e32 v98, v0
	v_mul_f32_e32 v0, 0xbfb8aa3b, v97
	v_exp_f32_e32 v0, v0
	v_pk_mul_f32 v[100:101], v[132:133], v[90:91] op_sel_hi:[1,0]
	v_cvt_pk_bf16_f32 v86, v86, v87
	v_pk_mul_f32 v[88:89], v[100:101], v[88:89]
	v_add_f32_e32 v0, 1.0, v0
	v_rcp_f32_e32 v99, v0
	s_nop 0
	v_pk_mul_f32 v[96:97], v[98:99], v[96:97]
	s_nop 0
	v_pk_mul_f32 v[88:89], v[88:89], v[96:97]
	s_nop 0
	v_cvt_pk_bf16_f32 v87, v88, v89
	global_store_dwordx2 v[92:93], v[86:87], off offset:192
	s_nop 0
	s_waitcnt vmcnt(2)
	s_nop 1
	v_mov_b32_e32 v86, v236
	v_mov_b32_e32 v87, v237
	v_mov_b32_e32 v88, v238
	v_mov_b32_e32 v89, v239
	v_mov_b32_e32 v94, v242
	v_mov_b32_e32 v95, v243
	v_pk_mul_f32 v[82:83], v[82:83], v[86:87]
	v_lshlrev_b32_e32 v96, 16, v94
	v_mul_f32_e32 v0, 0xbfb8aa3b, v96
	v_exp_f32_e32 v0, v0
	v_and_b32_e32 v97, 0xffff0000, v94
	v_pk_mul_f32 v[84:85], v[84:85], v[88:89]
	v_add_f32_e32 v0, 1.0, v0
	v_rcp_f32_e32 v98, v0
	v_mul_f32_e32 v0, 0xbfb8aa3b, v97
	v_exp_f32_e32 v0, v0
	s_nop 0
	v_add_f32_e32 v0, 1.0, v0
	v_rcp_f32_e32 v99, v0
	s_nop 0
	v_pk_mul_f32 v[86:87], v[98:99], v[96:97]
	s_nop 0
	v_pk_mul_f32 v[82:83], v[82:83], v[86:87]
	v_lshlrev_b32_e32 v86, 16, v95
	v_mul_f32_e32 v0, 0xbfb8aa3b, v86
	v_exp_f32_e32 v0, v0
	v_and_b32_e32 v87, 0xffff0000, v95
	v_cvt_pk_bf16_f32 v82, v82, v83
	v_add_f32_e32 v0, 1.0, v0
	v_rcp_f32_e32 v94, v0
	v_mul_f32_e32 v0, 0xbfb8aa3b, v87
	v_exp_f32_e32 v0, v0
	s_nop 0
	v_add_f32_e32 v0, 1.0, v0
	v_rcp_f32_e32 v95, v0
	s_nop 0
	v_pk_mul_f32 v[86:87], v[94:95], v[86:87]
	s_nop 0
	v_pk_mul_f32 v[84:85], v[84:85], v[86:87]
	v_mov_b64_e32 v[88:89], v[76:77]
	v_cvt_pk_bf16_f32 v83, v84, v85
	global_store_dwordx2 v[92:93], v[82:83], off offset:224
	v_mov_b64_e32 v[84:85], v[80:81]
	v_mov_b64_e32 v[92:93], v[72:73]
	v_mov_b64_e32 v[96:97], v[68:69]
	v_mov_b64_e32 v[82:83], v[78:79]
	v_mov_b64_e32 v[86:87], v[74:75]
	v_mov_b64_e32 v[90:91], v[70:71]
	v_mov_b64_e32 v[94:95], v[66:67]
	s_barrier
	s_cbranch_vccz .LBB0_876
